# out-proj K loop: first fragment reads of each half step issued right after the barrier, ahead of the DMA issue
# baseline (speedup 1.0000x reference)
.LBB0_76:
	ds_read_b128 v[114:117], v127 offset:16384
	ds_read_b128 v[118:121], v0
	ds_read_b128 v[166:169], v127 offset:18432
	ds_read_b128 v[170:173], v127 offset:20480
	ds_read_b128 v[174:177], v127 offset:22528
	ds_read_b128 v[238:241], v0 offset:2048
	ds_read_b128 v[242:245], v0 offset:4096
	ds_read_b128 v[246:249], v0 offset:6144
	s_and_b32 s12, s11, 12
	s_cmp_eq_u32 s12, 8
	s_cselect_b64 s[38:39], -1, 0
	s_cmp_lg_u32 s12, 8
	s_mov_b64 s[40:41], -1
	s_cbranch_scc0 .LBB0_78
	v_readfirstlane_b32 s12, v122
	s_nop 0
	s_add_u32 m0, s12, 0x9000
	s_nop 0
	global_load_lds_dwordx4 v185, s[48:49]
	s_add_u32 m0, s12, 0xd000
	s_nop 0
	global_load_lds_dwordx4 v185, s[100:101]
	s_add_u32 m0, s12, 0x9400
	s_nop 0
	global_load_lds_dwordx4 v188, s[48:49]
	s_add_u32 m0, s12, 0xd400
	s_nop 0
	global_load_lds_dwordx4 v188, s[100:101]
	s_add_u32 m0, s12, 0x9800
	s_nop 0
	global_load_lds_dwordx4 v193, s[48:49]
	s_add_u32 m0, s12, 0xd800
	s_nop 0
	global_load_lds_dwordx4 v193, s[100:101]
	s_add_u32 m0, s12, 0x9c00
	s_nop 0
	global_load_lds_dwordx4 v194, s[48:49]
	s_add_u32 m0, s12, 0xdc00
	s_nop 0
	global_load_lds_dwordx4 v194, s[100:101]
	v_add_u32_e32 v185, 0x80, v185
	v_add_u32_e32 v188, 0x80, v188
	v_add_u32_e32 v193, 0x80, v193
	v_add_u32_e32 v194, 0x80, v194
	s_mov_b64 s[40:41], 0

.LBB0_80:
	s_andn2_b64 vcc, exec, s[38:39]
	s_waitcnt lgkmcnt(3)
	v_mfma_f32_16x16x32_bf16 v[78:81], v[114:117], v[118:121], v[78:81]
	ds_read_b128 v[230:233], v129 offset:16384
	ds_read_b128 v[234:237], v129 offset:22528
	ds_read_b128 v[90:93], v129 offset:18432
	ds_read_b128 v[94:97], v129 offset:20480
	v_mfma_f32_16x16x32_bf16 v[74:77], v[166:169], v[118:121], v[74:77]
	v_mfma_f32_16x16x32_bf16 v[70:73], v[170:173], v[118:121], v[70:73]
	v_mfma_f32_16x16x32_bf16 v[66:69], v[174:177], v[118:121], v[66:69]
	s_waitcnt lgkmcnt(6)
	v_mfma_f32_16x16x32_bf16 v[62:65], v[114:117], v[238:241], v[62:65]
	v_mfma_f32_16x16x32_bf16 v[58:61], v[166:169], v[238:241], v[58:61]
	v_mfma_f32_16x16x32_bf16 v[54:57], v[170:173], v[238:241], v[54:57]
	v_mfma_f32_16x16x32_bf16 v[50:53], v[174:177], v[238:241], v[50:53]
	ds_read_b128 v[238:241], v128 offset:2048
	s_waitcnt lgkmcnt(6)
	v_mfma_f32_16x16x32_bf16 v[218:221], v[114:117], v[242:245], v[46:49]
	v_mfma_f32_16x16x32_bf16 v[222:225], v[166:169], v[242:245], v[42:45]
	v_mfma_f32_16x16x32_bf16 v[226:229], v[170:173], v[242:245], v[38:41]
	v_mfma_f32_16x16x32_bf16 v[118:121], v[174:177], v[242:245], v[34:37]
	s_nop 2
	ds_read_b128 v[34:37], v128
	ds_read_b128 v[242:245], v128 offset:4096
	s_waitcnt lgkmcnt(7)
	v_mfma_f32_16x16x32_bf16 v[114:117], v[114:117], v[246:249], v[30:33]
	v_mfma_f32_16x16x32_bf16 v[166:169], v[166:169], v[246:249], v[26:29]
	v_mfma_f32_16x16x32_bf16 v[170:173], v[170:173], v[246:249], v[22:25]
	v_mfma_f32_16x16x32_bf16 v[18:21], v[174:177], v[246:249], v[18:21]
	ds_read_b128 v[246:249], v128 offset:6144
	s_waitcnt lgkmcnt(2)
	v_mfma_f32_16x16x32_bf16 v[22:25], v[230:233], v[34:37], v[78:81]
	v_mfma_f32_16x16x32_bf16 v[26:29], v[90:93], v[34:37], v[74:77]
	v_mfma_f32_16x16x32_bf16 v[30:33], v[94:97], v[34:37], v[70:73]
	v_mfma_f32_16x16x32_bf16 v[34:37], v[234:237], v[34:37], v[66:69]
	v_mfma_f32_16x16x32_bf16 v[38:41], v[230:233], v[238:241], v[62:65]
	v_mfma_f32_16x16x32_bf16 v[42:45], v[90:93], v[238:241], v[58:61]
	v_mfma_f32_16x16x32_bf16 v[46:49], v[94:97], v[238:241], v[54:57]
	v_mfma_f32_16x16x32_bf16 v[50:53], v[234:237], v[238:241], v[50:53]
	s_waitcnt lgkmcnt(1)
	v_mfma_f32_16x16x32_bf16 v[54:57], v[230:233], v[242:245], v[218:221]
	v_mfma_f32_16x16x32_bf16 v[58:61], v[90:93], v[242:245], v[222:225]
	v_mfma_f32_16x16x32_bf16 v[62:65], v[94:97], v[242:245], v[226:229]
	v_mfma_f32_16x16x32_bf16 v[66:69], v[234:237], v[242:245], v[118:121]
	s_waitcnt lgkmcnt(0)
	v_mfma_f32_16x16x32_bf16 v[70:73], v[230:233], v[246:249], v[114:117]
	v_mfma_f32_16x16x32_bf16 v[74:77], v[90:93], v[246:249], v[166:169]
	v_mfma_f32_16x16x32_bf16 v[78:81], v[94:97], v[246:249], v[170:173]
	v_mfma_f32_16x16x32_bf16 v[18:21], v[234:237], v[246:249], v[18:21]
	s_cbranch_vccnz .LBB0_82
	s_waitcnt vmcnt(0)
	ds_write_b16 v130, v2 offset:36864
	ds_write_b16_d16_hi v130, v2 offset:36992
	ds_write_b16 v131, v3 offset:36864
	ds_write_b16_d16_hi v132, v3 offset:36864
	ds_write_b16 v133, v4 offset:36864
	ds_write_b16_d16_hi v134, v4 offset:36864
	ds_write_b16 v135, v5 offset:36864
	ds_write_b16_d16_hi v136, v5 offset:36864
	ds_write_b16 v137, v6 offset:36864
	ds_write_b16_d16_hi v137, v6 offset:36992
	ds_write_b16 v138, v7 offset:36864
	ds_write_b16_d16_hi v139, v7 offset:36864
	ds_write_b16 v140, v8 offset:36864
	ds_write_b16_d16_hi v141, v8 offset:36864
	ds_write_b16 v142, v9 offset:36864
	ds_write_b16_d16_hi v143, v9 offset:36864
	ds_write_b16 v144, v10 offset:36864
	ds_write_b16_d16_hi v144, v10 offset:36992
	ds_write_b16 v145, v11 offset:36864
	ds_write_b16_d16_hi v154, v11 offset:36864
	ds_write_b16 v155, v12 offset:36864
	ds_write_b16_d16_hi v156, v12 offset:36864
	ds_write_b16 v157, v13 offset:36864
	ds_write_b16_d16_hi v158, v13 offset:36864
	ds_write_b16 v159, v14 offset:36864
	ds_write_b16_d16_hi v159, v14 offset:36992
	ds_write_b16 v160, v15 offset:36864
	ds_write_b16_d16_hi v161, v15 offset:36864
	ds_write_b16 v162, v16 offset:36864
	ds_write_b16_d16_hi v163, v16 offset:36864
	ds_write_b16 v164, v17 offset:36864
	ds_write_b16_d16_hi v165, v17 offset:36864
.LBB0_82:
	s_add_i32 s12, s11, 2
	s_waitcnt vmcnt(0)
	s_cmp_gt_u32 s11, 13
	s_cselect_b64 s[38:39], -1, 0
	s_mov_b64 s[40:41], 0
	s_and_b64 vcc, exec, s[38:39]
	s_waitcnt vmcnt(0) lgkmcnt(0)
	s_barrier
	ds_read_b128 v[106:109], v127 offset:53248
	ds_read_b128 v[110:113], v0 offset:36864
	ds_read_b128 v[114:117], v127 offset:55296
	ds_read_b128 v[118:121], v127 offset:57344
	ds_read_b128 v[166:169], v127 offset:59392
	ds_read_b128 v[238:241], v0 offset:38912
	ds_read_b128 v[242:245], v0 offset:40960
	ds_read_b128 v[246:249], v0 offset:43008
	s_cbranch_vccnz .LBB0_87
	s_and_b32 s11, s12, 28
	s_mov_b64 s[14:15], 0xe600100
	s_mov_b64 s[40:41], -1
	s_cmp_lg_u32 s11, 8
	s_cbranch_scc0 .LBB0_85
	v_readfirstlane_b32 s11, v122
	s_nop 0
	s_add_u32 m0, s11, 0x0
	s_nop 0
	global_load_lds_dwordx4 v185, s[48:49]
	s_add_u32 m0, s11, 0x4000
	s_nop 0
	global_load_lds_dwordx4 v185, s[100:101]
	s_add_u32 m0, s11, 0x400
	s_nop 0
	global_load_lds_dwordx4 v188, s[48:49]
	s_add_u32 m0, s11, 0x4400
	s_nop 0
	global_load_lds_dwordx4 v188, s[100:101]
	s_add_u32 m0, s11, 0x800
	s_nop 0
	global_load_lds_dwordx4 v193, s[48:49]
	s_add_u32 m0, s11, 0x4800
	s_nop 0
	global_load_lds_dwordx4 v193, s[100:101]
	s_add_u32 m0, s11, 0xc00
	s_nop 0
	global_load_lds_dwordx4 v194, s[48:49]
	s_add_u32 m0, s11, 0x4c00
	s_nop 0
	global_load_lds_dwordx4 v194, s[100:101]
	v_add_u32_e32 v185, 0x80, v185
	v_add_u32_e32 v188, 0x80, v188
	v_add_u32_e32 v193, 0x80, v193
	v_add_u32_e32 v194, 0x80, v194
	s_mov_b64 s[40:41], 0

.LBB0_87:
	s_andn2_b64 vcc, exec, s[40:41]
	s_waitcnt lgkmcnt(3)
	v_mfma_f32_16x16x32_bf16 v[22:25], v[106:109], v[110:113], v[22:25]
	ds_read_b128 v[222:225], v129 offset:53248
	ds_read_b128 v[226:229], v129 offset:59392
	ds_read_b128 v[90:93], v129 offset:55296
	ds_read_b128 v[94:97], v129 offset:57344
	v_mfma_f32_16x16x32_bf16 v[26:29], v[114:117], v[110:113], v[26:29]
	v_mfma_f32_16x16x32_bf16 v[30:33], v[118:121], v[110:113], v[30:33]
	v_mfma_f32_16x16x32_bf16 v[34:37], v[166:169], v[110:113], v[34:37]
	s_waitcnt lgkmcnt(6)
	v_mfma_f32_16x16x32_bf16 v[38:41], v[106:109], v[238:241], v[38:41]
	v_mfma_f32_16x16x32_bf16 v[42:45], v[114:117], v[238:241], v[42:45]
	v_mfma_f32_16x16x32_bf16 v[46:49], v[118:121], v[238:241], v[46:49]
	v_mfma_f32_16x16x32_bf16 v[50:53], v[166:169], v[238:241], v[50:53]
	ds_read_b128 v[238:241], v128 offset:38912
	s_waitcnt lgkmcnt(6)
	v_mfma_f32_16x16x32_bf16 v[170:173], v[106:109], v[242:245], v[54:57]
	v_mfma_f32_16x16x32_bf16 v[174:177], v[114:117], v[242:245], v[58:61]
	v_mfma_f32_16x16x32_bf16 v[218:221], v[118:121], v[242:245], v[62:65]
	v_mfma_f32_16x16x32_bf16 v[110:113], v[166:169], v[242:245], v[66:69]
	s_nop 2
	ds_read_b128 v[54:57], v128 offset:36864
	ds_read_b128 v[242:245], v128 offset:40960
	s_waitcnt lgkmcnt(7)
	v_mfma_f32_16x16x32_bf16 v[106:109], v[106:109], v[246:249], v[70:73]
	v_mfma_f32_16x16x32_bf16 v[114:117], v[114:117], v[246:249], v[74:77]
	v_mfma_f32_16x16x32_bf16 v[118:121], v[118:121], v[246:249], v[78:81]
	v_mfma_f32_16x16x32_bf16 v[18:21], v[166:169], v[246:249], v[18:21]
	ds_read_b128 v[246:249], v128 offset:43008
	s_waitcnt lgkmcnt(2)
	v_mfma_f32_16x16x32_bf16 v[78:81], v[222:225], v[54:57], v[22:25]
	v_mfma_f32_16x16x32_bf16 v[74:77], v[90:93], v[54:57], v[26:29]
	v_mfma_f32_16x16x32_bf16 v[70:73], v[94:97], v[54:57], v[30:33]
	v_mfma_f32_16x16x32_bf16 v[66:69], v[226:229], v[54:57], v[34:37]
	v_mfma_f32_16x16x32_bf16 v[62:65], v[222:225], v[238:241], v[38:41]
	v_mfma_f32_16x16x32_bf16 v[58:61], v[90:93], v[238:241], v[42:45]
	v_mfma_f32_16x16x32_bf16 v[54:57], v[94:97], v[238:241], v[46:49]
	v_mfma_f32_16x16x32_bf16 v[50:53], v[226:229], v[238:241], v[50:53]
	s_waitcnt lgkmcnt(1)
	v_mfma_f32_16x16x32_bf16 v[34:37], v[226:229], v[242:245], v[110:113]
	v_mfma_f32_16x16x32_bf16 v[46:49], v[222:225], v[242:245], v[170:173]
	v_mfma_f32_16x16x32_bf16 v[42:45], v[90:93], v[242:245], v[174:177]
	v_mfma_f32_16x16x32_bf16 v[38:41], v[94:97], v[242:245], v[218:221]
	s_waitcnt lgkmcnt(0)
	v_mfma_f32_16x16x32_bf16 v[30:33], v[222:225], v[246:249], v[106:109]
	v_mfma_f32_16x16x32_bf16 v[26:29], v[90:93], v[246:249], v[114:117]
	v_mfma_f32_16x16x32_bf16 v[22:25], v[94:97], v[246:249], v[118:121]
	v_mfma_f32_16x16x32_bf16 v[18:21], v[226:229], v[246:249], v[18:21]
	s_cbranch_vccnz .LBB0_75
	s_waitcnt vmcnt(0)
	ds_write_b16 v130, v2
	ds_write_b16_d16_hi v130, v2 offset:128
	ds_write_b16 v131, v3
	ds_write_b16_d16_hi v132, v3
	ds_write_b16 v133, v4
	ds_write_b16_d16_hi v134, v4
	ds_write_b16 v135, v5
	ds_write_b16_d16_hi v136, v5
	ds_write_b16 v137, v6
	ds_write_b16_d16_hi v137, v6 offset:128
	ds_write_b16 v138, v7
	ds_write_b16_d16_hi v139, v7
	ds_write_b16 v140, v8
	ds_write_b16_d16_hi v141, v8
	ds_write_b16 v142, v9
	ds_write_b16_d16_hi v143, v9
	ds_write_b16 v144, v10
	ds_write_b16_d16_hi v144, v10 offset:128
	ds_write_b16 v145, v11
	ds_write_b16_d16_hi v154, v11
	ds_write_b16 v155, v12
	ds_write_b16_d16_hi v156, v12
	ds_write_b16 v157, v13
	ds_write_b16_d16_hi v158, v13
	ds_write_b16 v159, v14
	ds_write_b16_d16_hi v159, v14 offset:128
	ds_write_b16 v160, v15
	ds_write_b16_d16_hi v161, v15
	ds_write_b16 v162, v16
	ds_write_b16_d16_hi v163, v16
	ds_write_b16 v164, v17
	ds_write_b16_d16_hi v165, v17
	s_branch .LBB0_75
